# SHIFT loop: row-independent mu / k_k quads loaded once before the loop; one load group per item, no second vmcnt(0) and no loop-top store wait
# speedup vs baseline: 1.0145x; 1.0112x over previous
.LBB0_2055:
	s_and_b64 vcc, exec, s[0:1]
	s_cbranch_vccz .LBB0_2071
	v_mov_b32_e32 v0, s63
	ds_read_b32 v0, v0
	s_add_i32 s0, s91, 0x20088
	v_mov_b32_e32 v1, s89
	v_mov_b32_e32 v2, s0
	s_add_i32 s0, s91, 0x2008c
	s_mov_b32 s53, s33
	ds_read_b32 v1, v1
	s_waitcnt lgkmcnt(0)
	v_readfirstlane_b32 s33, v0
	ds_read_b32 v0, v2
	v_mov_b32_e32 v2, s0
	s_add_i32 s0, s91, 0x200d8
	v_mov_b32_e32 v3, s0
	s_add_i32 s0, s91, 0x200dc
	v_mov_b32_e32 v4, s0
	ds_read_b32 v2, v2
	ds_read_b32 v3, v3
	ds_read_b32 v4, v4
	s_mov_b32 s2, 0x420000
	s_mov_b32 s50, s24
	v_readfirstlane_b32 s34, v1
	s_waitcnt lgkmcnt(0)
	v_readfirstlane_b32 s4, v0
	v_readfirstlane_b32 s5, v2
	v_readfirstlane_b32 s0, v3
	v_readfirstlane_b32 s1, v4
	v_cmp_gt_i32_e32 vcc, s2, v160
	s_and_saveexec_b64 s[2:3], vcc
	s_cbranch_execz .LBB0_2061
	v_readlane_b32 s20, v254, 26
	s_mul_i32 s6, s20, 0x3000
	s_add_u32 s6, s4, s6
	s_addc_u32 s7, s5, 0
	s_add_u32 s8, s33, 0x2100000
	s_addc_u32 s9, s34, 0
	s_add_u32 s10, s33, 0x4200000
	s_addc_u32 s11, s34, 0
	s_add_u32 s12, s33, 0x6300000
	s_addc_u32 s13, s34, 0
	s_add_u32 s14, s33, 0xa500000
	s_addc_u32 s15, s34, 0
	s_add_u32 s16, s33, 0xc600000
	s_addc_u32 s17, s34, 0
	s_mul_i32 s4, s88, 0x2100000
	s_add_u32 s18, s33, s4
	s_addc_u32 s19, s34, 0
	s_lshl_b32 s4, s20, 12
	s_add_u32 s20, s0, s4
	s_addc_u32 s21, s1, 0
	s_add_u32 s22, s33, 0x15c00000
	s_addc_u32 s23, s34, 0
	s_add_u32 s24, s6, 0x1000
	s_addc_u32 s25, s7, 0
	v_and_b32_e32 v0, 15, v162
	s_add_u32 s26, s6, 0x2000
	v_cmp_eq_u32_e64 s[4:5], 0, v0
	v_lshlrev_b32_e32 v0, 2, v162
	v_readlane_b32 s0, v254, 24
	s_addc_u32 s27, s7, 0
	v_lshl_add_u32 v4, s93, 11, v0
	s_lshl_b32 s35, s0, 11
	s_mov_b64 s[28:29], 0
	v_mov_b32_e32 v5, v160
	v_and_b32_e32 v62, 0x3fc, v4
	v_lshlrev_b32_e32 v62, 2, v62
	global_load_dwordx4 v[64:67], v62, s[24:25]
	global_load_dwordx4 v[68:71], v62, s[6:7]
	global_load_dwordx4 v[72:75], v62, s[26:27]
	global_load_dwordx4 v[76:79], v62, s[20:21]
	s_branch .LBB0_2059

.LBB0_2059:
	v_ashrrev_i32_e32 v0, 8, v5
	v_ashrrev_i32_e32 v1, 31, v0
	v_and_b32_e32 v6, 0x3fc, v4
	v_cmp_gt_i32_e32 vcc, s92, v0
	v_lshlrev_b64 v[8:9], 10, v[0:1]
	s_movk_i32 s0, 0xfc00
	v_cndmask_b32_e32 v7, v227, v238, vcc
	v_or_b32_e32 v8, v8, v6
	s_mov_b32 s1, -1
	v_and_b32_e32 v16, v7, v0
	v_lshl_add_u64 v[2:3], v[8:9], 0, s[0:1]
	s_mov_b64 s[0:1], 0x400
	v_cmp_eq_u32_e32 vcc, 0, v16
	v_lshl_add_u64 v[12:13], v[8:9], 0, s[0:1]
	v_cmp_eq_u32_e64 s[0:1], v16, v7
	v_cndmask_b32_e32 v11, v3, v9, vcc
	v_cndmask_b32_e32 v10, v2, v8, vcc
	v_lshlrev_b64 v[2:3], 1, v[8:9]
	v_cndmask_b32_e64 v9, v13, v9, s[0:1]
	v_cndmask_b32_e64 v8, v12, v8, s[0:1]
	v_lshlrev_b64 v[8:9], 1, v[8:9]
	v_lshl_add_u64 v[14:15], s[8:9], 0, v[2:3]
	v_lshlrev_b64 v[10:11], 1, v[10:11]
	v_lshl_add_u64 v[12:13], s[8:9], 0, v[8:9]
	global_load_dwordx2 v[20:21], v[14:15], off
	global_load_dwordx2 v[24:25], v[12:13], off
	v_lshl_add_u64 v[14:15], s[8:9], 0, v[10:11]
	v_lshl_add_u64 v[12:13], s[10:11], 0, v[2:3]
	global_load_dwordx2 v[22:23], v[14:15], off
	global_load_dwordx2 v[26:27], v[12:13], off
	v_lshl_add_u64 v[12:13], s[10:11], 0, v[10:11]
	v_lshl_add_u64 v[10:11], s[12:13], 0, v[10:11]
	global_load_dwordx2 v[28:29], v[12:13], off
	global_load_dwordx2 v[34:35], v[10:11], off
	v_lshl_add_u64 v[12:13], s[10:11], 0, v[8:9]
	global_load_dwordx2 v[30:31], v[12:13], off
	v_lshl_add_u64 v[8:9], s[12:13], 0, v[8:9]
	global_load_dwordx2 v[36:37], v[8:9], off
	v_lshl_add_u64 v[12:13], s[12:13], 0, v[2:3]
	v_lshlrev_b32_e32 v7, 2, v6
	global_load_dwordx2 v[32:33], v[12:13], off
	s_nop 0
	v_cndmask_b32_e64 v40, 0.5, 0, s[0:1]
	v_cndmask_b32_e64 v38, 0.5, 0, vcc
	v_lshl_add_u64 v[42:43], s[14:15], 0, v[2:3]
	s_waitcnt vmcnt(8)
	v_cvt_f32_f16_e32 v44, v20
	s_waitcnt vmcnt(7)
	v_cvt_f32_f16_e32 v48, v24
	v_cvt_f32_f16_sdwa v49, v24 dst_sel:DWORD dst_unused:UNUSED_PAD src0_sel:WORD_1
	v_cvt_f32_f16_e32 v24, v25
	v_cvt_f32_f16_sdwa v25, v25 dst_sel:DWORD dst_unused:UNUSED_PAD src0_sel:WORD_1
	s_waitcnt vmcnt(6)
	v_cvt_f32_f16_e32 v46, v22
	v_cvt_f32_f16_sdwa v47, v22 dst_sel:DWORD dst_unused:UNUSED_PAD src0_sel:WORD_1
	v_cvt_f32_f16_e32 v22, v23
	s_waitcnt vmcnt(4)
	v_cvt_f32_f16_e32 v52, v28
	v_cvt_f32_f16_sdwa v53, v28 dst_sel:DWORD dst_unused:UNUSED_PAD src0_sel:WORD_1
	v_cvt_f32_f16_e32 v28, v29
	s_waitcnt vmcnt(2)
	v_cvt_f32_f16_e32 v54, v30
	v_cvt_f32_f16_sdwa v55, v30 dst_sel:DWORD dst_unused:UNUSED_PAD src0_sel:WORD_1
	v_cvt_f32_f16_e32 v30, v31
	v_cvt_f32_f16_sdwa v31, v31 dst_sel:DWORD dst_unused:UNUSED_PAD src0_sel:WORD_1
	v_cvt_f32_f16_sdwa v29, v29 dst_sel:DWORD dst_unused:UNUSED_PAD src0_sel:WORD_1
	v_cvt_f32_f16_sdwa v23, v23 dst_sel:DWORD dst_unused:UNUSED_PAD src0_sel:WORD_1
	v_cvt_f32_f16_e32 v50, v26
	v_cvt_f32_f16_sdwa v51, v26 dst_sel:DWORD dst_unused:UNUSED_PAD src0_sel:WORD_1
	v_cvt_f32_f16_e32 v26, v27
	v_cvt_f32_f16_sdwa v27, v27 dst_sel:DWORD dst_unused:UNUSED_PAD src0_sel:WORD_1
	v_cvt_f32_f16_sdwa v45, v20 dst_sel:DWORD dst_unused:UNUSED_PAD src0_sel:WORD_1
	v_cvt_f32_f16_e32 v20, v21
	v_cvt_f32_f16_sdwa v21, v21 dst_sel:DWORD dst_unused:UNUSED_PAD src0_sel:WORD_1
	v_pk_mul_f32 v[54:55], v[40:41], v[54:55] op_sel_hi:[0,1]
	v_pk_mul_f32 v[30:31], v[40:41], v[30:31] op_sel_hi:[0,1]
	v_pk_mul_f32 v[48:49], v[40:41], v[48:49] op_sel_hi:[0,1]
	v_pk_mul_f32 v[24:25], v[40:41], v[24:25] op_sel_hi:[0,1]
	v_pk_fma_f32 v[28:29], v[38:39], v[28:29], v[30:31] op_sel_hi:[0,1,1]
	v_pk_fma_f32 v[30:31], v[38:39], v[52:53], v[54:55] op_sel_hi:[0,1,1]
	v_pk_fma_f32 v[22:23], v[38:39], v[22:23], v[24:25] op_sel_hi:[0,1,1]
	v_pk_fma_f32 v[24:25], v[38:39], v[46:47], v[48:49] op_sel_hi:[0,1,1]
	v_sub_f32_e32 v31, v31, v51
	v_sub_f32_e32 v30, v30, v50
	v_sub_f32_e32 v29, v29, v27
	v_sub_f32_e32 v28, v28, v26
	s_waitcnt vmcnt(1)
	v_cvt_f32_f16_e32 v60, v36
	v_cvt_f32_f16_sdwa v61, v36 dst_sel:DWORD dst_unused:UNUSED_PAD src0_sel:WORD_1
	v_cvt_f32_f16_e32 v36, v37
	v_cvt_f32_f16_sdwa v37, v37 dst_sel:DWORD dst_unused:UNUSED_PAD src0_sel:WORD_1
	v_sub_f32_e32 v25, v25, v45
	v_sub_f32_e32 v24, v24, v44
	s_waitcnt vmcnt(0)
	v_pk_fma_f32 v[26:27], v[66:67], v[28:29], v[26:27]
	v_pk_fma_f32 v[28:29], v[64:65], v[30:31], v[50:51]
	v_sub_f32_e32 v9, v23, v21
	v_sub_f32_e32 v8, v22, v20
	v_cvt_f32_f16_e32 v58, v34
	v_cvt_f32_f16_sdwa v59, v34 dst_sel:DWORD dst_unused:UNUSED_PAD src0_sel:WORD_1
	v_cvt_f32_f16_e32 v34, v35
	v_cvt_f32_f16_sdwa v35, v35 dst_sel:DWORD dst_unused:UNUSED_PAD src0_sel:WORD_1
	s_waitcnt vmcnt(0)
	v_pk_fma_f32 v[8:9], v[70:71], v[8:9], v[20:21]
	v_pk_fma_f32 v[10:11], v[68:69], v[24:25], v[44:45]
	v_cvt_f32_f16_e32 v56, v32
	v_cvt_f32_f16_sdwa v57, v32 dst_sel:DWORD dst_unused:UNUSED_PAD src0_sel:WORD_1
	v_cvt_f32_f16_e32 v32, v33
	v_cvt_f32_f16_sdwa v33, v33 dst_sel:DWORD dst_unused:UNUSED_PAD src0_sel:WORD_1
	v_cvt_pk_f16_f32 v9, v8, v9
	v_cvt_pk_f16_f32 v8, v10, v11
	global_store_dwordx2 v[42:43], v[8:9], off
	v_lshl_add_u64 v[8:9], s[16:17], 0, v[2:3]
	v_cvt_pk_f16_f32 v11, v26, v27
	v_cvt_pk_f16_f32 v10, v28, v29
	global_store_dwordx2 v[8:9], v[10:11], off
	v_pk_mul_f32 v[8:9], v[40:41], v[60:61] op_sel_hi:[0,1]
	v_pk_mul_f32 v[10:11], v[40:41], v[36:37] op_sel_hi:[0,1]
	v_pk_fma_f32 v[10:11], v[38:39], v[34:35], v[10:11] op_sel_hi:[0,1,1]
	v_pk_fma_f32 v[8:9], v[38:39], v[58:59], v[8:9] op_sel_hi:[0,1,1]
	v_sub_f32_e32 v9, v9, v57
	v_sub_f32_e32 v8, v8, v56
	v_sub_f32_e32 v11, v11, v33
	v_sub_f32_e32 v10, v10, v32
	v_pk_fma_f32 v[10:11], v[74:75], v[10:11], v[32:33]
	v_pk_fma_f32 v[8:9], v[72:73], v[8:9], v[56:57]
	v_lshl_add_u64 v[2:3], s[18:19], 0, v[2:3]
	v_cvt_pk_f16_f32 v11, v10, v11
	v_cvt_pk_f16_f32 v10, v8, v9
	global_store_dwordx2 v[2:3], v[10:11], off
	v_pk_mul_f32 v[2:3], v[78:79], v[26:27]
	v_pk_mul_f32 v[8:9], v[76:77], v[28:29]
	v_mul_f32_e32 v3, v3, v3
	v_mul_f32_e32 v7, v9, v9
	v_fmac_f32_e32 v7, v8, v8
	v_fmac_f32_e32 v3, v2, v2
	v_add_f32_e32 v2, v7, v3
	s_nop 1
	v_add_f32_dpp v2, v2, v2 quad_perm:[1,0,3,2] row_mask:0xf bank_mask:0xf bound_ctrl:1
	s_nop 1
	v_add_f32_dpp v2, v2, v2 quad_perm:[2,3,0,1] row_mask:0xf bank_mask:0xf bound_ctrl:1
	s_nop 1
	v_add_f32_dpp v2, v2, v2 row_half_mirror row_mask:0xf bank_mask:0xf bound_ctrl:1
	s_nop 1
	v_mov_b32_dpp v3, v2 row_mirror row_mask:0xf bank_mask:0xf bound_ctrl:1
	s_and_saveexec_b64 s[30:31], s[4:5]
	s_cbranch_execz .LBB0_2058
	v_add_f32_e32 v2, v2, v3
	s_mov_b32 s0, 0xf800000
	v_mul_f32_e32 v3, 0x4f800000, v2
	v_cmp_gt_f32_e32 vcc, s0, v2
	v_lshlrev_b64 v[0:1], 6, v[0:1]
	v_lshl_add_u64 v[0:1], s[22:23], 0, v[0:1]
	v_cndmask_b32_e32 v2, v2, v3, vcc
	v_sqrt_f32_e32 v3, v2
	v_lshrrev_b32_e32 v152, 4, v6
	v_lshl_add_u64 v[0:1], v[0:1], 0, v[152:153]
	v_add_u32_e32 v7, -1, v3
	v_fma_f32 v9, -v7, v3, v2
	v_add_u32_e32 v8, 1, v3
	v_cmp_ge_f32_e64 s[0:1], 0, v9
	s_nop 1
	v_cndmask_b32_e64 v7, v3, v7, s[0:1]
	v_fma_f32 v3, -v8, v3, v2
	v_cmp_lt_f32_e64 s[0:1], 0, v3
	s_nop 1
	v_cndmask_b32_e64 v3, v7, v8, s[0:1]
	v_mul_f32_e32 v7, 0x37800000, v3
	v_cndmask_b32_e32 v3, v3, v7, vcc
	v_cmp_class_f32_e32 vcc, v2, v228
	s_nop 1
	v_cndmask_b32_e32 v2, v3, v2, vcc
	v_max_f32_e32 v2, 0x2b8cbccc, v2
	v_div_scale_f32 v3, s[0:1], v2, v2, 1.0
	v_rcp_f32_e32 v7, v3
	s_nop 0
	v_fma_f32 v8, -v3, v7, 1.0
	v_fmac_f32_e32 v7, v8, v7
	v_div_scale_f32 v8, vcc, 1.0, v2, 1.0
	v_mul_f32_e32 v9, v8, v7
	v_fma_f32 v10, -v3, v9, v8
	v_fmac_f32_e32 v9, v10, v7
	v_fma_f32 v3, -v3, v9, v8
	v_div_fmas_f32 v3, v3, v7, v9
	v_div_fixup_f32 v2, v3, v2, 1.0
	global_store_dword v[0:1], v2, off
	s_branch .LBB0_2058
